# attention, XCD-local mode: first-round tickets static (queue 0 fully static: long unit = workgroup index, short unit on the second visit for index < 8; queue 1 first visit = workgroup index, later vis
# speedup vs baseline: 1.0195x; 1.0097x over previous
; template <int Q>
; DI void attn_queue(const Params& p, int l, char* smem, int* s_unit, int cb) {
;     const bool ctxu = l < DEPTH - 1;
;     const int total = (Q == 0) ? (ctxu ? 576 : 512) : (Q == 1) ? (ctxu ? 960 : 768) : 768;
;     for (;;) {
;         if (threadIdx.x == 0) *s_unit = (int)atomicAdd(p.ctr + cb + l * 4 + Q, 1u);
;         __syncthreads();
;         const int u = *s_unit;
;         __syncthreads();
;         if (u >= total) break;
;         if (Q == 0) {
;             int b, head, qt, t1 = 0, n1 = 36;
;             if (u < 512) { b = u >> 6; head = (u >> 4) & 3; qt = u & 15; }
;             else { const int v = u - 512; b = v >> 3; head = (v >> 1) & 3; qt = 16 + (v & 1); t1 = 32; n1 = 4; }
.LBB0_69:
	s_andn2_b64 vcc, exec, s[4:5]
	s_cbranch_vccnz .LBB0_136
	s_cmp_lt_i32 s60, 3
	s_cselect_b64 s[44:45], -1, 0
	s_and_b64 s[4:5], s[44:45], exec
	s_movk_i32 s4, 0x240
	s_cselect_b32 s28, s4, 0x200
	s_lshl_b32 s4, s60, 6
	s_and_b32 s48, s99, -4
	s_ashr_i32 s5, s4, 31
	s_ashr_i32 s49, s48, 31
	s_ashr_i32 s61, s60, 31
	s_lshl_b64 s[46:47], s[4:5], 2
	v_writelane_b32 v255, 0, 45
	s_branch .LBB0_72

; template <int Q>
; DI void attn_queue(const Params& p, int l, char* smem, int* s_unit, int cb) {
;     ...
;     for (;;) {
;         if (threadIdx.x == 0) *s_unit = (int)atomicAdd(p.ctr + cb + l * 4 + Q, 1u);
;         __syncthreads();
;         const int u = *s_unit;
;         __syncthreads();
;         if (u >= total) break;
;         if (Q == 0) {
;             int b, head, qt, t1 = 0, n1 = 36;
;             if (u < 512) { b = u >> 6; head = (u >> 4) & 3; qt = u & 15; }
;             else { const int v = u - 512; b = v >> 3; head = (v >> 1) & 3; qt = 16 + (v & 1); t1 = 32; n1 = 4; }
;             attn_unit<0>(p, l, b, head, qt, head * 64, 256 + head * 64, head * 64, 768 + head * 64, head * 64, t1, n1, 0, 0, smem);
.LBB0_72:
	s_and_saveexec_b64 s[4:5], s[54:55]
	s_cbranch_execz .LBB0_76
	s_mov_b64 s[8:9], exec
	v_mbcnt_lo_u32_b32 v0, s8, 0
	v_mbcnt_hi_u32_b32 v0, s9, v0
	v_cmp_eq_u32_e32 vcc, 0, v0
	s_and_saveexec_b64 s[6:7], vcc
	s_cbranch_execz .LBB0_75
	ds_read_b32 v2, v193 offset:8
	s_load_dwordx2 s[34:35], s[0:1], 0x100
	s_lshl_b64 s[40:41], s[48:49], 2
	s_waitcnt lgkmcnt(0)
	s_add_u32 s34, s34, s40
	s_addc_u32 s35, s35, s41
	v_readfirstlane_b32 s40, v2
	s_nop 0
	s_cmp_eq_u32 s40, 0
	s_cbranch_scc1 .Lq0_glob
	v_readlane_b32 s8, v254, 0
	s_nop 0
	s_lshr_b32 s35, s8, 3
	s_and_b32 s8, s8, 7
	v_readlane_b32 s9, v255, 45
	s_nop 0
	s_add_i32 s40, s9, 1
	v_writelane_b32 v255, s40, 45
	s_add_i32 s40, s35, 64
	s_cmp_lt_u32 s35, 8
	s_cselect_b32 s40, s40, 0x7fff
	s_cmp_eq_u32 s9, 1
	s_cselect_b32 s40, s40, 0x7fff
	s_cmp_eq_u32 s9, 0
	s_cselect_b32 s9, s35, s40
	s_lshr_b32 s40, s28, 3
	s_lshl_b32 s34, s8, 6
	s_add_i32 s34, s34, s9
	s_lshl_b32 s35, s8, 3
	s_add_i32 s35, s35, s9
	s_addk_i32 s35, 0x1c0
	s_cmp_lt_u32 s9, 64
	s_cselect_b32 s34, s34, s35
	s_cmp_lt_u32 s9, s40
	s_cselect_b32 s34, s34, s28
	v_mov_b32_e32 v1, s34
	s_branch .LBB0_75

; template <int Q>
; DI void attn_queue(const Params& p, int l, char* smem, int* s_unit, int cb) {
;     ...
;         } else if (Q == 1) {
;             int b, head, qt, t1 = 0, n1 = 36; bool cgrp = false;
;             if (u < 768) { b = u / 96; head = (u >> 4) % 6; qt = u & 15; }
;             else if (u < 864) { const int v = u - 768; b = v / 12; head = (v >> 1) % 6; qt = 16 + (v & 1); t1 = 32; n1 = 4; }
.LBB0_84:
	s_and_b64 s[4:5], s[44:45], exec
	s_movk_i32 s4, 0x3c0
	s_cselect_b32 s28, s4, 0x300
	s_movk_i32 s61, 0x800
	v_writelane_b32 v255, 0, 46
	s_branch .LBB0_86

; template <int Q>
; DI void attn_queue(const Params& p, int l, char* smem, int* s_unit, int cb) {
;     ...
;     for (;;) {
;         if (threadIdx.x == 0) *s_unit = (int)atomicAdd(p.ctr + cb + l * 4 + Q, 1u);
;         __syncthreads();
;         const int u = *s_unit;
;         __syncthreads();
;         if (u >= total) break;
;         if (Q == 0) {
;             int b, head, qt, t1 = 0, n1 = 36;
;             if (u < 512) { b = u >> 6; head = (u >> 4) & 3; qt = u & 15; }
;             else { const int v = u - 512; b = v >> 3; head = (v >> 1) & 3; qt = 16 + (v & 1); t1 = 32; n1 = 4; }
;             attn_unit<0>(p, l, b, head, qt, head * 64, 256 + head * 64, head * 64, 768 + head * 64, head * 64, t1, n1, 0, 0, smem);
;         } else if (Q == 1) {
;             int b, head, qt, t1 = 0, n1 = 36; bool cgrp = false;
;             if (u < 768) { b = u / 96; head = (u >> 4) % 6; qt = u & 15; }
;             else if (u < 864) { const int v = u - 768; b = v / 12; head = (v >> 1) % 6; qt = 16 + (v & 1); t1 = 32; n1 = 4; }
;             else { const int v = u - 864; b = v / 12; head = (v >> 1) % 6; qt = 16 + (v & 1); t1 = 32; n1 = 4; cgrp = true; }
;             int qcol, kcol, vfeat, gcol, mixcol;
;             if (!cgrp) { const int kv = head / 3; qcol = 1024 + head * 64; kcol = 1408 + kv * 64; vfeat = 256 + kv * 64; gcol = 1664 + head * 64; mixcol = 256 + head * 64; }
;             else { qcol = 2048 + head * 64; kcol = 2432 + head * 64; vfeat = 384 + head * 64; gcol = 3200 + head * 64; mixcol = 640 + head * 64; }
;             attn_unit<1>(p, l, b, head, qt, qcol, kcol, vfeat, gcol, mixcol, t1, n1, 0, 0, smem);
.LBB0_86:
	s_and_saveexec_b64 s[4:5], s[54:55]
	s_cbranch_execz .LBB0_90
	s_mov_b64 s[8:9], exec
	v_mbcnt_lo_u32_b32 v0, s8, 0
	v_mbcnt_hi_u32_b32 v0, s9, v0
	v_cmp_eq_u32_e32 vcc, 0, v0
	s_and_saveexec_b64 s[6:7], vcc
	s_cbranch_execz .LBB0_89
	ds_read_b32 v2, v193 offset:8
	s_load_dwordx2 s[34:35], s[0:1], 0x100
	s_lshl_b64 s[40:41], s[48:49], 2
	s_waitcnt lgkmcnt(0)
	s_add_u32 s34, s34, s40
	s_addc_u32 s35, s35, s41
	v_readfirstlane_b32 s40, v2
	s_nop 0
	s_cmp_eq_u32 s40, 0
	s_cbranch_scc1 .Lq1_glob
	v_readlane_b32 s8, v254, 0
	s_nop 0
	s_lshr_b32 s40, s8, 3
	s_and_b32 s8, s8, 7
	v_readlane_b32 s9, v255, 46
	s_nop 0
	s_cmp_eq_u32 s9, 0
	s_cbranch_scc0 .Lq1_dyn
	v_writelane_b32 v255, 1, 46
	s_mov_b32 s9, s40
	s_branch .Lq1_conv
.Lq1_dyn:
	s_lshl_b32 s9, s8, 8
	s_lshl_b32 s40, s60, 4
	s_add_i32 s9, s9, s40
	s_addk_i32 s9, 0x2424
	s_add_u32 s34, s68, s9
	s_addc_u32 s35, s69, 0
	v_mov_b32_e32 v1, 1
	global_atomic_add v1, v193, v1, s[34:35] sc0
	s_waitcnt vmcnt(0)
	v_readfirstlane_b32 s9, v1
	s_nop 0
	s_add_i32 s9, s9, 64
.Lq1_conv:
	s_lshr_b32 s40, s28, 3
	s_mul_i32 s35, s8, 12
	s_add_i32 s35, s35, s9
	s_mul_i32 s34, s8, 0x60
	s_add_i32 s34, s34, s9
	s_add_i32 s8, s35, 0x2a0
	s_cmp_lt_u32 s9, 0x60
	s_cselect_b32 s34, s34, s8
	s_add_i32 s8, s35, 0x2f4
	s_cmp_lt_u32 s9, 0x6c
	s_cselect_b32 s34, s34, s8
	s_cmp_lt_u32 s9, s40
	s_cselect_b32 s34, s34, s28
	v_mov_b32_e32 v1, s34
	s_branch .LBB0_89
